# bar_last + never-executed padding restoring the MFMA loops' baseline placement
# speedup vs baseline: 1.0020x; 1.0020x over previous
; #define PG8_STAGE(bufoff, gbase, voff) do { _Pragma("unroll") for (int _i = 0; _i < 2; ++_i) \
;         __builtin_amdgcn_global_load_lds((const unsigned*)((const char*)(gbase) + (voff)[_i]), (LAS unsigned*)(lds + (bufoff) + ldsw + _i * 8192), 16, 0, 0); } while (0)
; #define PG8_WAIT_V(n) asm volatile("s_waitcnt vmcnt(" #n ")" ::: "memory")
; #define PG8_BAR __builtin_amdgcn_s_barrier()
; template <class Epi, class Sched>
; __device__ __forceinline__ void gemm_phase(LAS unsigned char* lds, const Gemm g, const Sched& S, const Epi& E) {
;     ...
;     f32x4 acc[2][2][4][2];
; #pragma unroll
;     for (int a = 0; a < 2; ++a)
; #pragma unroll
;         for (int b = 0; b < 2; ++b)
; #pragma unroll
;             for (int m = 0; m < 4; ++m)
; #pragma unroll
;                 for (int n = 0; n < 2; ++n) acc[a][b][m][n] = (f32x4){0.f, 0.f, 0.f, 0.f};
;     bf16x8 At[4][2], B0[2][2], B1[2][2];
;     const char* cA = (const char*)g.A + (size_t)cur.pm * tstepA + (size_t)cur.ka * 2; const char* cB = (const char*)g.Bt + (size_t)cur.pn * tstepB;
;     S.a_ready(cur);
;     PG8_STAGE(PG8_SB(0, 0), cB, voffB); PG8_STAGE(PG8_SB(0, 1), cB + hstepB, voffB); PG8_STAGE(PG8_SA(0, 0), cA, voffA); PG8_STAGE(PG8_SA(0, 1), cA + hstepA, voffA);
;     if (wr == 1) PG8_BAR;
;     PG8_WAIT_V(2); PG8_BAR;
;     PG8_STAGE(PG8_SB(1, 0), cB + kstep, voffB); PG8_STAGE(PG8_SA(1, 0), cA + kstep, voffA); PG8_STAGE(PG8_SB(1, 1), cB + hstepB + kstep, voffB);
;     PG8_WAIT_V(6); PG8_BAR;
.LBB0_267:
	v_lshl_add_u64 v[14:15], s[24:25], 0, v[4:5]
	v_mov_b32_e32 v3, v5
	v_and_b32_e32 v142, 15, v143
	v_and_b32_e32 v22, 48, v143
	v_lshlrev_b32_e32 v23, 2, v143
	v_lshl_add_u64 v[16:17], s[24:25], 0, v[2:3]
	s_and_b32 s48, s44, 3
	v_lshl_or_b32 v22, v142, 6, v22
	s_lshl_b32 s4, s47, 13
	v_and_b32_e32 v23, 32, v23
	s_add_i32 m0, s50, 0x18000
	v_lshl_add_u64 v[14:15], v[14:15], 0, s[36:37]
	v_lshl_add_u64 v[18:19], s[20:21], 0, v[4:5]
	v_bitop3_b32 v24, v22, s4, v23 bitop3:0xde
	s_lshl_b32 s4, s48, 12
	s_waitcnt vmcnt(2)
	s_barrier
	global_load_lds_dwordx4 v[14:15], off
	v_lshl_add_u64 v[14:15], v[16:17], 0, s[36:37]
	s_add_i32 m0, s50, 0x1a000
	s_add_i32 s54, s50, 0x8000
	s_add_i32 s55, s50, 0xa000
	v_lshl_add_u64 v[20:21], s[20:21], 0, v[2:3]
	v_bitop3_b32 v144, v22, s4, v23 bitop3:0xde
	global_load_lds_dwordx4 v[14:15], off
	v_lshl_add_u64 v[14:15], v[18:19], 0, s[36:37]
	s_mov_b32 m0, s54
	s_add_u32 s4, s24, 0x158080
	global_load_lds_dwordx4 v[14:15], off
	v_lshl_add_u64 v[14:15], v[20:21], 0, s[36:37]
	s_mov_b32 m0, s55
	s_addc_u32 s5, s25, 0
	global_load_lds_dwordx4 v[14:15], off
	s_add_i32 m0, s50, 0x1c000
	v_lshl_add_u64 v[14:15], s[4:5], 0, v[4:5]
	global_load_lds_dwordx4 v[14:15], off
	v_lshl_add_u64 v[14:15], s[4:5], 0, v[2:3]
	s_add_i32 m0, s50, 0x1e000
	s_movk_i32 s10, 0x1580
	global_load_lds_dwordx4 v[14:15], off
	v_lshrrev_b32_e32 v11, 1, v11
	v_mul_lo_u32 v10, v10, s10
	s_mov_b32 s22, 0x15800
	v_mad_u64_u32 v[10:11], s[4:5], v11, s22, v[10:11]
	v_or_b32_e32 v10, v10, v12
	v_add_lshl_u32 v134, v10, v13, 1
	v_lshrrev_b32_e32 v10, 1, v6
	v_mul_lo_u32 v6, v7, s10
	v_mad_u64_u32 v[6:7], s[4:5], v10, s22, v[6:7]
	s_waitcnt vmcnt(6)
	v_or_b32_e32 v6, v6, v8
	s_cmpk_lt_u32 s45, 0x100
	v_add_lshl_u32 v136, v6, v9, 1
	v_mov_b32_e32 v6, 0
	v_readlane_b32 s4, v254, 13
	s_cselect_b64 s[18:19], -1, 0
	v_mov_b32_e32 v135, v5
	v_mov_b32_e32 v137, v5
	s_mov_b32 s59, 0
	v_add_u32_e32 v145, 0, v24
	s_mov_b32 s10, s4
	v_readlane_b32 s46, v253, 61
	v_mov_b32_e32 v7, v6
	v_mov_b32_e32 v8, v6
	v_mov_b32_e32 v9, v6
	v_mov_b32_e32 v10, v6
	v_mov_b32_e32 v11, v6
	v_mov_b32_e32 v12, v6
	v_mov_b32_e32 v13, v6
	v_mov_b32_e32 v14, v6
	v_mov_b32_e32 v15, v6
	v_mov_b32_e32 v16, v6
	v_mov_b32_e32 v17, v6
	v_mov_b32_e32 v18, v6
	v_mov_b32_e32 v19, v6
	v_mov_b32_e32 v20, v6
	v_mov_b32_e32 v21, v6
	v_mov_b32_e32 v22, v6
	v_mov_b32_e32 v23, v6
	v_mov_b32_e32 v24, v6
	v_mov_b32_e32 v25, v6
	v_mov_b32_e32 v30, v6
	v_mov_b32_e32 v31, v6
	v_mov_b32_e32 v32, v6
	v_mov_b32_e32 v33, v6
	v_mov_b32_e32 v38, v6
	v_mov_b32_e32 v39, v6
	v_mov_b32_e32 v40, v6
	v_mov_b32_e32 v41, v6
	v_mov_b32_e32 v46, v6
	v_mov_b32_e32 v47, v6
	v_mov_b32_e32 v48, v6
	v_mov_b32_e32 v49, v6
	v_mov_b32_e32 v26, v6
	v_mov_b32_e32 v27, v6
	v_mov_b32_e32 v28, v6
	v_mov_b32_e32 v29, v6
	v_mov_b32_e32 v34, v6
	v_mov_b32_e32 v35, v6
	v_mov_b32_e32 v36, v6
	v_mov_b32_e32 v37, v6
	v_mov_b32_e32 v42, v6
	v_mov_b32_e32 v43, v6
	v_mov_b32_e32 v44, v6
	v_mov_b32_e32 v45, v6
	v_mov_b32_e32 v50, v6
	v_mov_b32_e32 v51, v6
	v_mov_b32_e32 v52, v6
	v_mov_b32_e32 v53, v6
	v_mov_b32_e32 v54, v6
	v_mov_b32_e32 v55, v6
	v_mov_b32_e32 v56, v6
	v_mov_b32_e32 v57, v6
	v_mov_b32_e32 v58, v6
	v_mov_b32_e32 v59, v6
	v_mov_b32_e32 v60, v6
	v_mov_b32_e32 v61, v6
	v_mov_b32_e32 v62, v6
	v_mov_b32_e32 v63, v6
	v_mov_b32_e32 v64, v6
	v_mov_b32_e32 v65, v6
	v_mov_b32_e32 v66, v6
	v_mov_b32_e32 v67, v6
	v_mov_b32_e32 v68, v6
	v_mov_b32_e32 v69, v6
	v_mov_b32_e32 v70, v6
	v_mov_b32_e32 v71, v6
	v_mov_b32_e32 v72, v6
	v_mov_b32_e32 v73, v6
	v_mov_b32_e32 v74, v6
	v_mov_b32_e32 v75, v6
	v_mov_b32_e32 v76, v6
	v_mov_b32_e32 v77, v6
	v_mov_b32_e32 v78, v6
	v_mov_b32_e32 v79, v6
	v_mov_b32_e32 v80, v6
	v_mov_b32_e32 v81, v6
	v_mov_b32_e32 v82, v6
	v_mov_b32_e32 v83, v6
	v_mov_b32_e32 v84, v6
	v_mov_b32_e32 v85, v6
	v_mov_b32_e32 v86, v6
	v_mov_b32_e32 v87, v6
	v_mov_b32_e32 v88, v6
	v_mov_b32_e32 v89, v6
	v_mov_b32_e32 v94, v6
	v_mov_b32_e32 v95, v6
	v_mov_b32_e32 v96, v6
	v_mov_b32_e32 v97, v6
	v_mov_b32_e32 v102, v6
	v_mov_b32_e32 v103, v6
	v_mov_b32_e32 v104, v6
	v_mov_b32_e32 v105, v6
	v_mov_b32_e32 v114, v6
	v_mov_b32_e32 v115, v6
	v_mov_b32_e32 v116, v6
	v_mov_b32_e32 v117, v6
	v_mov_b32_e32 v90, v6
	v_mov_b32_e32 v91, v6
	v_mov_b32_e32 v92, v6
	v_mov_b32_e32 v93, v6
	v_mov_b32_e32 v98, v6
	v_mov_b32_e32 v99, v6
	v_mov_b32_e32 v100, v6
	v_mov_b32_e32 v101, v6
	v_mov_b32_e32 v106, v6
	v_mov_b32_e32 v107, v6
	v_mov_b32_e32 v108, v6
	v_mov_b32_e32 v109, v6
	v_mov_b32_e32 v110, v6
	v_mov_b32_e32 v111, v6
	v_mov_b32_e32 v112, v6
	v_mov_b32_e32 v113, v6
	v_mov_b32_e32 v118, v6
	v_mov_b32_e32 v119, v6
	v_mov_b32_e32 v120, v6
	v_mov_b32_e32 v121, v6
	v_mov_b32_e32 v122, v6
	v_mov_b32_e32 v123, v6
	v_mov_b32_e32 v124, v6
	v_mov_b32_e32 v125, v6
	v_mov_b32_e32 v126, v6
	v_mov_b32_e32 v127, v6
	v_mov_b32_e32 v128, v6
	v_mov_b32_e32 v129, v6
	v_mov_b32_e32 v130, v6
	v_mov_b32_e32 v131, v6
	v_mov_b32_e32 v132, v6
	v_mov_b32_e32 v133, v6
	s_barrier
	s_branch .LBB0_270
	s_nop 0
	s_nop 0
	s_nop 0
	s_nop 0
	s_nop 0
	s_nop 0
	s_nop 0
	s_nop 0
	s_nop 0
	s_nop 0
	s_nop 0
	s_nop 0
	s_nop 0
	s_nop 0
	s_nop 0
	s_nop 0
	s_nop 0
	s_nop 0
	s_nop 0
	s_nop 0
	s_nop 0
	s_nop 0
	s_nop 0
	s_nop 0
	s_nop 0
	s_nop 0

; #define PG8_STAGE(bufoff, gbase, voff) do { _Pragma("unroll") for (int _i = 0; _i < 2; ++_i) \
;         __builtin_amdgcn_global_load_lds((const unsigned*)((const char*)(gbase) + (voff)[_i]), (LAS unsigned*)(lds + (bufoff) + ldsw + _i * 8192), 16, 0, 0); } while (0)
; #define PG8_WAIT_V(n) asm volatile("s_waitcnt vmcnt(" #n ")" ::: "memory")
; #define PG8_BAR __builtin_amdgcn_s_barrier()
; template <class Epi, class Sched>
; __device__ __forceinline__ void gemm_phase(LAS unsigned char* lds, const Gemm g, const Sched& S, const Epi& E) {
;     ...
;     const char* cA = (const char*)g.A + (size_t)cur.pm * tstepA + (size_t)cur.ka * 2; const char* cB = (const char*)g.Bt + (size_t)cur.pn * tstepB;
;     S.a_ready(cur);
;     PG8_STAGE(PG8_SB(0, 0), cB, voffB); PG8_STAGE(PG8_SB(0, 1), cB + hstepB, voffB); PG8_STAGE(PG8_SA(0, 0), cA, voffA); PG8_STAGE(PG8_SA(0, 1), cA + hstepA, voffA);
;     if (wr == 1) PG8_BAR;
;     PG8_WAIT_V(2); PG8_BAR;
;     PG8_STAGE(PG8_SB(1, 0), cB + kstep, voffB); PG8_STAGE(PG8_SA(1, 0), cA + kstep, voffA); PG8_STAGE(PG8_SB(1, 1), cB + hstepB + kstep, voffB);
;     PG8_WAIT_V(6); PG8_BAR;
.LBB0_507:
	v_lshrrev_b32_e32 v20, 1, v4
	v_and_b32_e32 v20, 24, v20
	v_and_b32_e32 v21, 15, v4
	v_lshlrev_b32_e32 v22, 1, v20
	v_lshlrev_b32_e32 v4, 2, v4
	s_and_b32 s20, s17, 3
	v_lshl_or_b32 v235, s18, 6, v21
	v_lshl_or_b32 v21, v21, 6, v22
	s_lshl_b32 s17, s18, 13
	v_and_b32_e32 v4, 32, v4
	s_add_i32 m0, s50, 0x18000
	v_lshl_add_u64 v[12:13], v[12:13], 0, s[36:37]
	v_bitop3_b32 v22, v21, s17, v4 bitop3:0xde
	s_lshl_b32 s17, s20, 12
	s_waitcnt vmcnt(2)
	s_barrier
	global_load_lds_dwordx4 v[12:13], off
	v_lshl_add_u64 v[10:11], v[10:11], 0, s[36:37]
	s_add_i32 m0, s50, 0x1a000
	s_add_i32 s54, s50, 0x8000
	s_add_i32 s55, s50, 0xa000
	global_load_lds_dwordx4 v[10:11], off
	v_lshl_add_u64 v[6:7], v[6:7], 0, s[36:37]
	s_mov_b32 m0, s54
	s_add_u32 s18, s42, 0x80080
	global_load_lds_dwordx4 v[6:7], off
	v_lshl_add_u64 v[6:7], v[8:9], 0, s[36:37]
	s_mov_b32 m0, s55
	s_addc_u32 s19, s43, 0
	global_load_lds_dwordx4 v[6:7], off
	s_add_i32 m0, s50, 0x1c000
	v_lshl_add_u64 v[6:7], s[18:19], 0, v[212:213]
	global_load_lds_dwordx4 v[6:7], off
	v_lshl_add_u64 v[6:7], s[18:19], 0, v[216:217]
	s_add_i32 m0, s50, 0x1e000
	v_bitop3_b32 v236, v21, s17, v4 bitop3:0xde
	global_load_lds_dwordx4 v[6:7], off
	v_lshlrev_b32_e32 v4, 2, v20
	v_lshl_add_u64 v[218:219], s[12:13], 0, v[4:5]
	v_lshl_add_u64 v[220:221], s[10:11], 0, v[4:5]
	v_lshl_add_u64 v[222:223], s[14:15], 0, v[4:5]
	v_lshlrev_b32_e32 v4, 15, v14
	v_and_b32_e32 v4, 0xffff0000, v4
	v_lshl_add_u32 v4, v15, 12, v4
	v_and_b32_e32 v6, 1, v14
	v_lshl_or_b32 v4, v6, 6, v4
	v_lshl_add_u32 v224, v16, 1, v4
	v_lshlrev_b32_e32 v4, 15, v17
	v_and_b32_e32 v4, 0xffff0000, v4
	s_waitcnt vmcnt(6)
	v_lshl_add_u32 v4, v18, 12, v4
	v_and_b32_e32 v6, 1, v17
	s_cmpk_lt_u32 s16, 0x100
	v_lshl_or_b32 v4, v6, 6, v4
	s_cselect_b64 s[16:17], -1, 0
	s_lshl_b32 s56, s20, 6
	v_mov_b32_e32 v225, v5
	v_lshl_add_u32 v226, v19, 1, v4
	v_mov_b32_e32 v227, v5
	s_mov_b32 s57, 0
	v_add_u32_e32 v237, 0, v22
	v_lshlrev_b32_e32 v4, 1, v20
	s_barrier
	s_branch .LBB0_510
	s_nop 0
	s_nop 0
	s_nop 0
	s_nop 0
	s_nop 0
	s_nop 0
	s_nop 0
	s_nop 0
	s_nop 0
	s_nop 0
	s_nop 0
	s_nop 0
	s_nop 0
	s_nop 0
	s_nop 0
	s_nop 0
	s_nop 0
	s_nop 0
	s_nop 0
	s_nop 0
	s_nop 0
	s_nop 0
	s_nop 0
	s_nop 0
	s_nop 0
	s_nop 0
	s_nop 0
	s_nop 0
	s_nop 0
	s_nop 0
	s_nop 0
	s_nop 0
	s_nop 0
	s_nop 0
	s_nop 0
	s_nop 0
	s_nop 0
	s_nop 0
	s_nop 0
	s_nop 0
	s_nop 0
	s_nop 0
	s_nop 0
	s_nop 0
	s_nop 0
	s_nop 0
	s_nop 0
	s_nop 0
	s_nop 0
	s_nop 0
	s_nop 0
	s_nop 0
	s_nop 0
	s_nop 0
	s_nop 0
	s_nop 0
	s_nop 0
	s_nop 0
	s_nop 0
	s_nop 0
	s_nop 0
	s_nop 0

; #define PG8_STAGE(bufoff, gbase, voff) do { _Pragma("unroll") for (int _i = 0; _i < 2; ++_i) \
;         __builtin_amdgcn_global_load_lds((const unsigned*)((const char*)(gbase) + (voff)[_i]), (LAS unsigned*)(lds + (bufoff) + ldsw + _i * 8192), 16, 0, 0); } while (0)
; #define PG8_WAIT_V(n) asm volatile("s_waitcnt vmcnt(" #n ")" ::: "memory")
; #define PG8_BAR __builtin_amdgcn_s_barrier()
; template <class Epi, class Sched>
; __device__ __forceinline__ void gemm_phase(LAS unsigned char* lds, const Gemm g, const Sched& S, const Epi& E) {
;     ...
;     const char* cA = (const char*)g.A + (size_t)cur.pm * tstepA + (size_t)cur.ka * 2; const char* cB = (const char*)g.Bt + (size_t)cur.pn * tstepB;
;     S.a_ready(cur);
;     PG8_STAGE(PG8_SB(0, 0), cB, voffB); PG8_STAGE(PG8_SB(0, 1), cB + hstepB, voffB); PG8_STAGE(PG8_SA(0, 0), cA, voffA); PG8_STAGE(PG8_SA(0, 1), cA + hstepA, voffA);
;     if (wr == 1) PG8_BAR;
;     PG8_WAIT_V(2); PG8_BAR;
;     PG8_STAGE(PG8_SB(1, 0), cB + kstep, voffB); PG8_STAGE(PG8_SA(1, 0), cA + kstep, voffA); PG8_STAGE(PG8_SB(1, 1), cB + hstepB + kstep, voffB);
;     PG8_WAIT_V(6); PG8_BAR;
.LBB0_649:
	s_add_u32 s8, s14, 0xd000000
	v_lshrrev_b32_e32 v20, 1, v4
	s_addc_u32 s9, s15, 0
	v_and_b32_e32 v189, 15, v4
	v_and_b32_e32 v21, 24, v20
	s_add_u32 s10, s14, 0x100000
	v_lshlrev_b32_e32 v20, 1, v21
	v_lshlrev_b32_e32 v22, 6, v189
	v_lshlrev_b32_e32 v4, 2, v4
	s_addc_u32 s11, s15, 0
	s_and_b32 s18, s13, 3
	v_or_b32_e32 v23, v22, v20
	s_lshl_b32 s13, s16, 13
	v_and_b32_e32 v4, 32, v4
	s_add_i32 m0, s47, 0x18000
	v_lshl_add_u64 v[12:13], v[12:13], 0, s[36:37]
	s_lshl_b32 s51, s16, 6
	v_bitop3_b32 v24, v23, s13, v4 bitop3:0xde
	s_lshl_b32 s13, s18, 12
	s_waitcnt vmcnt(2)
	s_barrier
	global_load_lds_dwordx4 v[12:13], off
	v_lshl_add_u64 v[10:11], v[10:11], 0, s[36:37]
	s_add_i32 m0, s47, 0x1a000
	s_add_i32 s52, s47, 0x8000
	s_add_i32 s53, s47, 0xa000
	global_load_lds_dwordx4 v[10:11], off
	v_lshl_add_u64 v[6:7], v[6:7], 0, s[36:37]
	s_mov_b32 m0, s52
	s_add_u32 s16, s28, 0x80080
	global_load_lds_dwordx4 v[6:7], off
	v_lshl_add_u64 v[6:7], v[8:9], 0, s[36:37]
	s_mov_b32 m0, s53
	s_addc_u32 s17, s29, 0
	global_load_lds_dwordx4 v[6:7], off
	s_add_i32 m0, s47, 0x1c000
	v_lshl_add_u64 v[6:7], s[16:17], 0, v[182:183]
	global_load_lds_dwordx4 v[6:7], off
	v_lshl_add_u64 v[6:7], s[16:17], 0, v[186:187]
	s_add_i32 m0, s47, 0x1e000
	v_lshl_or_b32 v188, s18, 5, v21
	global_load_lds_dwordx4 v[6:7], off
	v_bitop3_b32 v231, v23, s13, v4 bitop3:0xde
	v_lshlrev_b32_e32 v4, 2, v188
	v_lshl_add_u64 v[6:7], s[14:15], 0, v[4:5]
	s_mov_b64 s[16:17], 0x200000
	s_cmpk_lt_u32 s12, 0x100
	v_lshl_add_u64 v[190:191], v[6:7], 0, s[16:17]
	s_mov_b64 s[16:17], 0x600000
	s_cselect_b64 s[12:13], -1, 0
	v_lshl_add_u64 v[192:193], v[6:7], 0, s[16:17]
	s_lshl_b32 s16, s18, 10
	s_add_u32 s14, s14, s16
	s_addc_u32 s15, s15, 0
	v_mov_b32_e32 v23, v5
	v_lshl_add_u64 v[6:7], s[14:15], 0, v[22:23]
	v_mov_b32_e32 v21, v5
	v_lshlrev_b32_e32 v4, 15, v14
	v_lshl_add_u64 v[6:7], v[6:7], 0, v[20:21]
	s_mov_b64 s[14:15], 0x5000000
	v_and_b32_e32 v4, 0xffff0000, v4
	v_lshl_add_u64 v[194:195], v[6:7], 0, s[14:15]
	v_lshl_add_u32 v4, v15, 12, v4
	v_and_b32_e32 v6, 1, v14
	v_lshl_or_b32 v4, v6, 6, v4
	v_lshl_add_u32 v196, v16, 1, v4
	v_lshlrev_b32_e32 v4, 15, v17
	v_and_b32_e32 v4, 0xffff0000, v4
	s_waitcnt vmcnt(6)
	v_lshl_add_u32 v4, v18, 12, v4
	v_and_b32_e32 v6, 1, v17
	v_lshl_or_b32 v4, v6, 6, v4
	v_mov_b32_e32 v197, v5
	v_lshl_add_u32 v212, v19, 1, v4
	v_mov_b32_e32 v213, v5
	s_mov_b32 s54, 0
	v_add_u32_e32 v235, 0, v24
	s_barrier
	s_branch .LBB0_652
	s_nop 0
	s_nop 0
	s_nop 0
	s_nop 0
	s_nop 0
	s_nop 0
	s_nop 0
	s_nop 0
	s_nop 0
	s_nop 0
	s_nop 0
	s_nop 0
	s_nop 0
	s_nop 0
	s_nop 0
	s_nop 0
	s_nop 0
	s_nop 0
	s_nop 0
	s_nop 0
	s_nop 0
	s_nop 0
	s_nop 0
	s_nop 0
	s_nop 0
	s_nop 0
	s_nop 0
	s_nop 0
	s_nop 0
	s_nop 0
	s_nop 0
	s_nop 0
	s_nop 0
	s_nop 0
	s_nop 0
	s_nop 0
	s_nop 0
	s_nop 0
	s_nop 0
	s_nop 0
	s_nop 0
	s_nop 0
	s_nop 0
	s_nop 0
	s_nop 0
	s_nop 0
	s_nop 0
	s_nop 0
	s_nop 0
	s_nop 0
	s_nop 0
	s_nop 0
	s_nop 0
	s_nop 0
	s_nop 0
	s_nop 0

; #define PG8_STAGE(bufoff, gbase, voff) do { _Pragma("unroll") for (int _i = 0; _i < 2; ++_i) \
;         __builtin_amdgcn_global_load_lds((const unsigned*)((const char*)(gbase) + (voff)[_i]), (LAS unsigned*)(lds + (bufoff) + ldsw + _i * 8192), 16, 0, 0); } while (0)
; #define PG8_WAIT_V(n) asm volatile("s_waitcnt vmcnt(" #n ")" ::: "memory")
; #define PG8_BAR __builtin_amdgcn_s_barrier()
; template <class Epi, class Sched>
; __device__ __forceinline__ void gemm_phase(LAS unsigned char* lds, const Gemm g, const Sched& S, const Epi& E) {
;     ...
;     f32x4 acc[2][2][4][2];
; #pragma unroll
;     for (int a = 0; a < 2; ++a)
; #pragma unroll
;         for (int b = 0; b < 2; ++b)
; #pragma unroll
;             for (int m = 0; m < 4; ++m)
; #pragma unroll
;                 for (int n = 0; n < 2; ++n) acc[a][b][m][n] = (f32x4){0.f, 0.f, 0.f, 0.f};
;     bf16x8 At[4][2], B0[2][2], B1[2][2];
;     const char* cA = (const char*)g.A + (size_t)cur.pm * tstepA + (size_t)cur.ka * 2; const char* cB = (const char*)g.Bt + (size_t)cur.pn * tstepB;
;     S.a_ready(cur);
;     PG8_STAGE(PG8_SB(0, 0), cB, voffB); PG8_STAGE(PG8_SB(0, 1), cB + hstepB, voffB); PG8_STAGE(PG8_SA(0, 0), cA, voffA); PG8_STAGE(PG8_SA(0, 1), cA + hstepA, voffA);
;     if (wr == 1) PG8_BAR;
;     PG8_WAIT_V(2); PG8_BAR;
;     PG8_STAGE(PG8_SB(1, 0), cB + kstep, voffB); PG8_STAGE(PG8_SA(1, 0), cA + kstep, voffA); PG8_STAGE(PG8_SB(1, 1), cB + hstepB + kstep, voffB);
;     PG8_WAIT_V(6); PG8_BAR;
.LBB0_995:
	v_mov_b32_e32 v139, v5
	v_lshl_add_u64 v[10:11], s[24:25], 0, v[138:139]
	v_mov_b32_e32 v135, v5
	v_lshl_add_u64 v[12:13], s[24:25], 0, v[134:135]
	v_mov_b32_e32 v141, v5
	s_add_i32 m0, s58, 0x18000
	v_lshl_add_u64 v[10:11], v[10:11], 0, s[36:37]
	v_lshl_add_u64 v[18:19], s[26:27], 0, v[140:141]
	v_mov_b32_e32 v137, v5
	s_waitcnt vmcnt(2)
	s_barrier
	global_load_lds_dwordx4 v[10:11], off
	v_lshl_add_u64 v[10:11], v[12:13], 0, s[36:37]
	s_add_i32 m0, s58, 0x1a000
	s_add_i32 s62, s58, 0x8000
	v_lshl_add_u64 v[20:21], s[26:27], 0, v[136:137]
	global_load_lds_dwordx4 v[10:11], off
	v_lshl_add_u64 v[10:11], v[18:19], 0, s[36:37]
	s_mov_b32 m0, s62
	s_add_i32 s63, s58, 0xa000
	v_lshl_add_u64 v[14:15], s[4:5], 0, v[138:139]
	global_load_lds_dwordx4 v[10:11], off
	v_lshl_add_u64 v[10:11], v[20:21], 0, s[36:37]
	s_mov_b32 m0, s63
	v_lshl_add_u64 v[16:17], s[4:5], 0, v[134:135]
	global_load_lds_dwordx4 v[10:11], off
	s_add_i32 m0, s58, 0x1c000
	v_lshl_add_u64 v[10:11], v[14:15], 0, s[36:37]
	global_load_lds_dwordx4 v[10:11], off
	v_lshl_add_u64 v[10:11], v[16:17], 0, s[36:37]
	s_add_i32 m0, s58, 0x1e000
	v_and_b32_e32 v168, 15, v169
	global_load_lds_dwordx4 v[10:11], off
	v_and_b32_e32 v9, 48, v169
	v_lshlrev_b32_e32 v10, 2, v169
	s_and_b32 s54, s50, 3
	s_lshr_b32 s64, s6, 6
	v_lshl_or_b32 v9, v168, 6, v9
	s_lshl_b32 s4, s52, 13
	v_and_b32_e32 v10, 32, v10
	v_bitop3_b32 v11, v9, s4, v10 bitop3:0xde
	s_lshl_b32 s4, s54, 12
	s_add_i32 s65, s64, -2
	s_cmpk_lt_u32 s51, 0x100
	v_bitop3_b32 v148, v9, s4, v10 bitop3:0xde
	s_cselect_b64 s[28:29], -1, 0
	s_add_u32 s4, s34, 0x80
	v_add_u32_e32 v4, v8, v4
	s_addc_u32 s5, 0, 0
	v_add_lshl_u32 v4, v4, v7, 1
	v_add_u32_e32 v2, v6, v2
	v_lshl_add_u64 v[142:143], s[4:5], 0, v[4:5]
	v_add_lshl_u32 v4, v2, v3, 1
	s_waitcnt vmcnt(6)
	v_lshl_add_u64 v[144:145], s[4:5], 0, v[4:5]
	v_mov_b32_e32 v4, v5
	v_mov_b32_e32 v2, v5
	v_mov_b32_e32 v3, v5
	v_add_u32_e32 v149, 0, v11
	v_mov_b64_e32 v[8:9], v[4:5]
	v_mov_b64_e32 v[12:13], v[4:5]
	v_mov_b64_e32 v[16:17], v[4:5]
	v_mov_b64_e32 v[20:21], v[4:5]
	v_mov_b64_e32 v[24:25], v[4:5]
	v_mov_b64_e32 v[32:33], v[4:5]
	v_mov_b64_e32 v[40:41], v[4:5]
	v_mov_b64_e32 v[48:49], v[4:5]
	v_mov_b64_e32 v[28:29], v[4:5]
	v_mov_b64_e32 v[36:37], v[4:5]
	v_mov_b64_e32 v[44:45], v[4:5]
	v_mov_b64_e32 v[52:53], v[4:5]
	v_mov_b64_e32 v[56:57], v[4:5]
	v_mov_b64_e32 v[60:61], v[4:5]
	v_mov_b64_e32 v[64:65], v[4:5]
	v_mov_b64_e32 v[68:69], v[4:5]
	v_mov_b64_e32 v[72:73], v[4:5]
	v_mov_b64_e32 v[76:77], v[4:5]
	v_mov_b64_e32 v[80:81], v[4:5]
	v_mov_b64_e32 v[84:85], v[4:5]
	v_mov_b64_e32 v[88:89], v[4:5]
	v_mov_b64_e32 v[96:97], v[4:5]
	v_mov_b64_e32 v[104:105], v[4:5]
	v_mov_b64_e32 v[116:117], v[4:5]
	v_mov_b64_e32 v[92:93], v[4:5]
	v_mov_b64_e32 v[100:101], v[4:5]
	v_mov_b64_e32 v[108:109], v[4:5]
	v_mov_b64_e32 v[112:113], v[4:5]
	v_mov_b64_e32 v[120:121], v[4:5]
	v_mov_b64_e32 v[124:125], v[4:5]
	v_mov_b64_e32 v[128:129], v[4:5]
	v_mov_b64_e32 v[132:133], v[4:5]
	v_readlane_b32 s4, v254, 13
	s_mov_b32 s66, 0
	v_mov_b64_e32 v[6:7], v[2:3]
	v_mov_b64_e32 v[10:11], v[2:3]
	v_mov_b64_e32 v[14:15], v[2:3]
	v_mov_b64_e32 v[18:19], v[2:3]
	v_mov_b64_e32 v[22:23], v[2:3]
	v_mov_b64_e32 v[30:31], v[2:3]
	v_mov_b64_e32 v[38:39], v[2:3]
	v_mov_b64_e32 v[46:47], v[2:3]
	v_mov_b64_e32 v[26:27], v[2:3]
	v_mov_b64_e32 v[34:35], v[2:3]
	v_mov_b64_e32 v[42:43], v[2:3]
	v_mov_b64_e32 v[50:51], v[2:3]
	v_mov_b64_e32 v[54:55], v[2:3]
	v_mov_b64_e32 v[58:59], v[2:3]
	v_mov_b64_e32 v[62:63], v[2:3]
	v_mov_b64_e32 v[66:67], v[2:3]
	v_mov_b64_e32 v[70:71], v[2:3]
	v_mov_b64_e32 v[74:75], v[2:3]
	v_mov_b64_e32 v[78:79], v[2:3]
	v_mov_b64_e32 v[82:83], v[2:3]
	v_mov_b64_e32 v[86:87], v[2:3]
	v_mov_b64_e32 v[94:95], v[2:3]
	v_mov_b64_e32 v[102:103], v[2:3]
	v_mov_b64_e32 v[114:115], v[2:3]
	v_mov_b64_e32 v[90:91], v[2:3]
	v_mov_b64_e32 v[98:99], v[2:3]
	v_mov_b64_e32 v[106:107], v[2:3]
	v_mov_b64_e32 v[110:111], v[2:3]
	v_mov_b64_e32 v[118:119], v[2:3]
	v_mov_b64_e32 v[122:123], v[2:3]
	v_mov_b64_e32 v[126:127], v[2:3]
	v_mov_b64_e32 v[130:131], v[2:3]
	s_mov_b32 s6, s4
	v_readlane_b32 s53, v253, 61
	s_barrier
	s_branch .LBB0_998
	s_nop 0
	s_nop 0
	s_nop 0
	s_nop 0
	s_nop 0
	s_nop 0
	s_nop 0
	s_nop 0
	s_nop 0
	s_nop 0
	s_nop 0
	s_nop 0
	s_nop 0
	s_nop 0
	s_nop 0
	s_nop 0
	s_nop 0
	s_nop 0
	s_nop 0
	s_nop 0
	s_nop 0
	s_nop 0
	s_nop 0
	s_nop 0
	s_nop 0
	s_nop 0
	s_nop 0
	s_nop 0
	s_nop 0
	s_nop 0
	s_nop 0
	s_nop 0
	s_nop 0
	s_nop 0
	s_nop 0
	s_nop 0
	s_nop 0
	s_nop 0
	s_nop 0
	s_nop 0
	s_nop 0
	s_nop 0
	s_nop 0
	s_nop 0
	s_nop 0
	s_nop 0
	s_nop 0
	s_nop 0
